# LayerNorm phase (layer 0): the row's eight shift/scale pieces requested at the top of the iteration, counted waits instead of four vmcnt(0) per row
# speedup vs baseline: 1.0045x; 1.0045x over previous
; __device__ __forceinline__ void p_layernorm(const Args& A, int l) {
;     ...
;     for (int row = gw; row < MT; row += NGW) {
;         float* xr = A.out + (size_t)row * 1024 + 4 * lane;
;         f32x4 v[4]; float s = 0.f;
;         const int rown = row + NGW < MT ? row + NGW : row;
; #pragma unroll
;         for (int j = 0; j < 4; ++j) { v[j] = vn[j]; s += (v[j][0] + v[j][1]) + (v[j][2] + v[j][3]); }
; #pragma unroll
;         for (int j = 0; j < 4; ++j) vn[j] = *(const f32x4*)(A.out + (size_t)rown * 1024 + 4 * lane + 256 * j);
;         const float mean = wave_sum(s) * (1.0f / 1024.0f); float s2 = 0.f;
; #pragma unroll
;         for (int j = 0; j < 4; ++j) { v[j] = v[j] - mean; s2 += (v[j][0] * v[j][0] + v[j][1] * v[j][1]) + (v[j][2] * v[j][2] + v[j][3] * v[j][3]); }
;         const float rstd = 1.0f / sqrtf(wave_sum(s2) * (1.0f / 1024.0f) + 1e-5f);
; #pragma unroll
;         for (int j = 0; j < 4; ++j) { v[j] = v[j] * rstd * gv[j] + bv[j]; *(f32x4*)(xr + 256 * j) = v[j]; }
.LBB0_500:
	s_andn2_b64 vcc, exec, s[94:95]
	s_cbranch_vccnz .Lln_nomod
	v_ashrrev_i32_e32 v132, 13, v66
	v_mul_i32_i24_e32 v132, 0xc00, v132
	v_ashrrev_i32_e32 v133, 31, v132
	v_lshl_add_u64 v[132:133], v[132:133], 2, v[74:75]
	v_add_co_u32_e32 v134, vcc, 0x1000, v132
	s_nop 1
	v_addc_co_u32_e32 v135, vcc, 0, v133, vcc
	global_load_dwordx4 v[100:103], v[134:135], off
	global_load_dwordx4 v[104:107], v[132:133], off
	global_load_dwordx4 v[108:111], v[134:135], off offset:1024
	global_load_dwordx4 v[112:115], v[132:133], off offset:1024
	global_load_dwordx4 v[116:119], v[134:135], off offset:2048
	global_load_dwordx4 v[120:123], v[132:133], off offset:2048
	global_load_dwordx4 v[124:127], v[134:135], off offset:3072
	global_load_dwordx4 v[128:131], v[132:133], off offset:3072
.Lln_nomod:
	v_mov_b64_e32 v[84:85], v[34:35]
	v_pk_add_f32 v[48:49], v[54:55], v[44:45]
	v_mov_b64_e32 v[82:83], v[32:33]
	v_add_f32_e32 v33, v48, v49
	v_pk_add_f32 v[48:49], v[50:51], v[40:41]
	v_add_f32_e32 v43, 0, v33
	v_pk_add_f32 v[48:49], v[48:49], v[48:49] op_sel_hi:[0,1]
	v_add_f32_e32 v33, v36, v37
	v_add_f32_e32 v47, v38, v39
	v_mov_b32_e32 v35, v49
	v_pk_add_f32 v[32:33], v[32:33], v[46:47]
	v_pk_add_f32 v[34:35], v[34:35], v[42:43]
	v_add_u32_e32 v81, s24, v66
	v_pk_add_f32 v[32:33], v[32:33], v[34:35]
	v_cmp_gt_i32_e32 vcc, s97, v81
	v_add_f32_e32 v32, v32, v33
	ds_bpermute_b32 v33, v67, v32
	s_mov_b32 s4, 0xf800000
	s_waitcnt lgkmcnt(0)
	v_add_f32_e32 v32, v32, v33
	ds_bpermute_b32 v33, v76, v32
	s_waitcnt lgkmcnt(0)
	v_add_f32_e32 v32, v32, v33
	ds_bpermute_b32 v33, v77, v32
	s_waitcnt lgkmcnt(0)
	v_add_f32_e32 v32, v32, v33
	ds_bpermute_b32 v33, v78, v32
	s_waitcnt lgkmcnt(0)
	v_add_f32_e32 v32, v32, v33
	ds_bpermute_b32 v33, v79, v32
	s_waitcnt lgkmcnt(0)
	v_add_f32_e32 v32, v32, v33
	ds_bpermute_b32 v33, v80, v32
	s_waitcnt lgkmcnt(0)
	v_add_f32_e32 v52, v32, v33
	v_fmac_f32_e32 v54, 0xba800000, v52
	v_fmac_f32_e32 v45, 0xba800000, v52
	v_fmac_f32_e32 v55, 0xba800000, v52
	v_fmac_f32_e32 v50, 0xba800000, v52
	v_fmac_f32_e32 v41, 0xba800000, v52
	v_fmac_f32_e32 v51, 0xba800000, v52
	v_fmac_f32_e32 v44, 0xba800000, v52
	v_fmac_f32_e32 v40, 0xba800000, v52
	v_mov_b32_e32 v42, v55
	v_mov_b32_e32 v43, v45
	v_mov_b32_e32 v45, v54
	v_mov_b32_e32 v58, v51
	v_mov_b32_e32 v59, v41
	v_mov_b32_e32 v41, v50
	v_pk_mul_f32 v[32:33], v[42:43], v[42:43]
	v_pk_mul_f32 v[34:35], v[44:45], v[44:45]
	v_pk_mul_f32 v[46:47], v[58:59], v[58:59]
	v_pk_mul_f32 v[48:49], v[40:41], v[40:41]
	v_pk_mov_b32 v[50:51], v[34:35], v[32:33] op_sel:[1,0]
	v_mov_b32_e32 v35, v33
	v_pk_mov_b32 v[32:33], v[48:49], v[46:47] op_sel:[1,0]
	v_mov_b32_e32 v49, v47
	v_pk_add_f32 v[32:33], v[32:33], v[48:49]
	v_fmac_f32_e32 v36, 0xba800000, v52
	v_pk_add_f32 v[32:33], v[32:33], v[32:33] op_sel_hi:[0,1]
	v_fmac_f32_e32 v37, 0xba800000, v52
	v_fmac_f32_e32 v38, 0xba800000, v52
	v_mul_f32_e32 v32, v36, v36
	v_pk_add_f32 v[34:35], v[50:51], v[34:35]
	v_fmac_f32_e32 v39, 0xba800000, v52
	v_pk_fma_f32 v[46:47], v[36:37], v[36:37], v[32:33] op_sel_hi:[1,1,0]
	v_mul_f32_e32 v32, v38, v38
	v_pk_add_f32 v[34:35], v[34:35], v[34:35] op_sel_hi:[0,1]
	v_pk_fma_f32 v[48:49], v[38:39], v[38:39], v[32:33] op_sel_hi:[1,1,0]
	v_fmamk_f32 v85, v52, 0xba800000, v85
	v_fmamk_f32 v84, v52, 0xba800000, v84
	v_fmamk_f32 v83, v52, 0xba800000, v83
	v_fmac_f32_e32 v82, 0xba800000, v52
	v_mul_f32_e32 v46, v82, v82
	v_mul_f32_e32 v48, v83, v83
	v_mul_f32_e32 v34, v84, v84
	v_mul_f32_e32 v32, v85, v85
	v_pk_add_f32 v[46:47], v[46:47], v[48:49]
	v_pk_add_f32 v[32:33], v[34:35], v[32:33]
	s_nop 0
	v_pk_add_f32 v[32:33], v[46:47], v[32:33]
	s_nop 0
	v_add_f32_e32 v32, v32, v33
	ds_bpermute_b32 v33, v67, v32
	s_waitcnt lgkmcnt(0)
	v_add_f32_e32 v34, v32, v33
	ds_bpermute_b32 v35, v76, v34
	v_cndmask_b32_e32 v32, v66, v81, vcc
	v_ashrrev_i32_e32 v33, 31, v32
	v_lshlrev_b64 v[32:33], 12, v[32:33]
	v_lshl_add_u64 v[32:33], v[68:69], 0, v[32:33]
	s_waitcnt lgkmcnt(0)
	v_add_f32_e32 v60, v34, v35
	global_load_dwordx4 v[54:57], v[32:33], off
	global_load_dwordx4 v[50:53], v[32:33], off offset:1024
	global_load_dwordx4 v[46:49], v[32:33], off offset:2048
	s_nop 0
	global_load_dwordx4 v[32:35], v[32:33], off offset:3072
	ds_bpermute_b32 v61, v77, v60
	s_waitcnt lgkmcnt(0)
	v_add_f32_e32 v60, v60, v61
	ds_bpermute_b32 v61, v78, v60
	s_waitcnt lgkmcnt(0)
	v_add_f32_e32 v60, v60, v61
	ds_bpermute_b32 v61, v79, v60
	s_waitcnt lgkmcnt(0)
	v_add_f32_e32 v60, v60, v61
	ds_bpermute_b32 v61, v80, v60
	s_waitcnt lgkmcnt(0)
	v_add_f32_e32 v60, v60, v61
	v_mov_b32_e32 v61, 0x3727c5ac
	v_fmamk_f32 v60, v60, 0x3a800000, v61
	v_mul_f32_e32 v61, 0x4f800000, v60
	v_cmp_gt_f32_e32 vcc, s4, v60
	s_nop 1
	v_cndmask_b32_e32 v60, v60, v61, vcc
	v_sqrt_f32_e32 v61, v60
	s_nop 0
	v_add_u32_e32 v62, -1, v61
	v_fma_f32 v63, -v62, v61, v60
	v_cmp_ge_f32_e64 s[4:5], 0, v63
	v_add_u32_e32 v63, 1, v61
	s_nop 0
	v_cndmask_b32_e64 v62, v61, v62, s[4:5]
	v_fma_f32 v61, -v63, v61, v60
	v_cmp_lt_f32_e64 s[4:5], 0, v61
	s_nop 1
	v_cndmask_b32_e64 v61, v62, v63, s[4:5]
	v_mul_f32_e32 v62, 0x37800000, v61
	v_cndmask_b32_e32 v61, v61, v62, vcc
	v_cmp_class_f32_e32 vcc, v60, v216
	s_nop 1
	v_cndmask_b32_e32 v60, v61, v60, vcc
	v_div_scale_f32 v61, s[4:5], v60, v60, 1.0
	v_rcp_f32_e32 v62, v61
	s_movk_i32 s4, 0x7fff
	v_cmp_lt_i32_e64 s[4:5], s4, v81
	v_fma_f32 v63, -v61, v62, 1.0
	v_fmac_f32_e32 v62, v63, v62
	v_div_scale_f32 v63, vcc, 1.0, v60, 1.0
	v_mul_f32_e32 v64, v63, v62
	v_fma_f32 v65, -v61, v64, v63
	v_fmac_f32_e32 v64, v65, v62
	v_fma_f32 v61, -v61, v64, v63
	v_div_fmas_f32 v61, v61, v62, v64
	v_div_fixup_f32 v86, v61, v60, 1.0
	v_pk_mul_f32 v[42:43], v[42:43], v[86:87] op_sel_hi:[1,0]
	v_pk_mul_f32 v[40:41], v[40:41], v[86:87] op_sel_hi:[1,0]
	v_pk_fma_f32 v[64:65], v[2:3], v[42:43], v[10:11]
	v_pk_mul_f32 v[42:43], v[58:59], v[86:87] op_sel_hi:[1,0]
	v_pk_mul_f32 v[36:37], v[36:37], v[86:87] op_sel_hi:[1,0]
	v_pk_mul_f32 v[38:39], v[38:39], v[86:87] op_sel_hi:[1,0]
	v_pk_mul_f32 v[44:45], v[44:45], v[86:87] op_sel_hi:[1,0]
	v_pk_fma_f32 v[60:61], v[6:7], v[42:43], v[14:15]
	v_pk_fma_f32 v[58:59], v[4:5], v[40:41], v[12:13]
	v_pk_fma_f32 v[42:43], v[18:19], v[38:39], v[26:27]
	v_pk_fma_f32 v[40:41], v[16:17], v[36:37], v[24:25]
	v_pk_mul_f32 v[36:37], v[82:83], v[86:87] op_sel_hi:[1,0]
	v_pk_mul_f32 v[38:39], v[84:85], v[86:87] op_sel_hi:[1,0]
	v_pk_fma_f32 v[62:63], v[0:1], v[44:45], v[8:9]
	v_pk_fma_f32 v[38:39], v[22:23], v[38:39], v[30:31]
	v_pk_fma_f32 v[36:37], v[20:21], v[36:37], v[28:29]
	s_andn2_b64 vcc, exec, s[94:95]
	global_store_dwordx4 v[72:73], v[62:65], off
	global_store_dwordx4 v[72:73], v[58:61], off offset:1024
	global_store_dwordx4 v[72:73], v[40:43], off offset:2048
	global_store_dwordx4 v[72:73], v[36:39], off offset:3072
	s_cbranch_vccnz .LBB0_499
; __device__ __forceinline__ unsigned cvtpk(float lo, float hi) { f32x2_t v = {lo, hi}; bf16x2_t b = __builtin_convertvector(v, bf16x2_t); return __builtin_bit_cast(unsigned, b); }
; __device__ __forceinline__ void p_layernorm(const Args& A, int l) {
;     ...
;         const int rown = row + NGW < MT ? row + NGW : row;
; #pragma unroll
;         for (int j = 0; j < 4; ++j) { v[j] = vn[j]; s += (v[j][0] + v[j][1]) + (v[j][2] + v[j][3]); }
; #pragma unroll
;         for (int j = 0; j < 4; ++j) vn[j] = *(const f32x4*)(A.out + (size_t)rown * 1024 + 4 * lane + 256 * j);
;     ...
;         if (l + 1 < DEPTH) {
;             const float* mb = mod + (row >> 13) * 3072 + 4 * lane;
; #pragma unroll
;             for (int j = 0; j < 4; ++j) { const f32x4 sh = *(const f32x4*)(mb + 256 * j), sc = *(const f32x4*)(mb + 1024 + 256 * j);
;                 const f32x4 u = v[j] * (sc + 1.0f) + sh;
;                 *(u64*)(U + (size_t)row * 1024 + 4 * lane + 256 * j) = (u64)cvtpk(u[0], u[1]) | ((u64)cvtpk(u[2], u[3]) << 32); }
	s_waitcnt vmcnt(14)
	v_pk_add_f32 v[102:103], v[102:103], 1.0 op_sel_hi:[1,0]
	v_pk_add_f32 v[100:101], v[100:101], 1.0 op_sel_hi:[1,0]
	v_pk_fma_f32 v[64:65], v[64:65], v[102:103], v[106:107]
	v_pk_fma_f32 v[62:63], v[62:63], v[100:101], v[104:105]
	s_nop 0
	v_cvt_pk_bf16_f32 v62, v62, v63
	v_cvt_pk_bf16_f32 v63, v64, v65
	global_store_dwordx2 v[70:71], v[62:63], off
	s_waitcnt vmcnt(13)
	v_pk_add_f32 v[110:111], v[110:111], 1.0 op_sel_hi:[1,0]
	v_pk_add_f32 v[108:109], v[108:109], 1.0 op_sel_hi:[1,0]
	v_pk_fma_f32 v[60:61], v[60:61], v[110:111], v[114:115]
	v_pk_fma_f32 v[58:59], v[58:59], v[108:109], v[112:113]
	s_nop 0
	v_cvt_pk_bf16_f32 v58, v58, v59
	v_cvt_pk_bf16_f32 v59, v60, v61
	global_store_dwordx2 v[70:71], v[58:59], off offset:512
	s_waitcnt vmcnt(12)
	v_pk_add_f32 v[118:119], v[118:119], 1.0 op_sel_hi:[1,0]
	v_pk_add_f32 v[116:117], v[116:117], 1.0 op_sel_hi:[1,0]
	v_pk_fma_f32 v[42:43], v[42:43], v[118:119], v[122:123]
	v_pk_fma_f32 v[40:41], v[40:41], v[116:117], v[120:121]
	s_nop 0
	v_cvt_pk_bf16_f32 v40, v40, v41
	v_cvt_pk_bf16_f32 v41, v42, v43
	global_store_dwordx2 v[70:71], v[40:41], off offset:1024
	s_waitcnt vmcnt(11)
	v_pk_add_f32 v[126:127], v[126:127], 1.0 op_sel_hi:[1,0]
	v_pk_add_f32 v[124:125], v[124:125], 1.0 op_sel_hi:[1,0]
	v_pk_fma_f32 v[38:39], v[38:39], v[126:127], v[130:131]
	v_pk_fma_f32 v[36:37], v[36:37], v[124:125], v[128:129]
	s_nop 0
	v_cvt_pk_bf16_f32 v36, v36, v37
	v_cvt_pk_bf16_f32 v37, v38, v39
	global_store_dwordx2 v[70:71], v[36:37], off offset:1536
	s_and_b64 s[4:5], exec, s[4:5]
	s_or_b64 s[8:9], s[4:5], s[8:9]
	v_readlane_b32 s4, v255, 35
	v_readlane_b32 s5, v255, 36
	v_mov_b32_e32 v66, v81
	s_waitcnt vmcnt(11)
	v_mov_b32_e32 v44, v54
	v_lshl_add_u64 v[70:71], v[70:71], 0, s[4:5]
	v_readlane_b32 s4, v255, 37
	v_readlane_b32 s5, v255, 38
	v_mov_b32_e32 v54, v55
	v_mov_b32_e32 v55, v56
	v_lshl_add_u64 v[72:73], v[72:73], 0, s[4:5]
	v_mov_b32_e32 v45, v57
	s_waitcnt vmcnt(10)
	v_mov_b32_e32 v40, v50
	v_mov_b32_e32 v50, v51
	v_mov_b32_e32 v51, v52
	v_mov_b32_e32 v41, v53
	s_waitcnt vmcnt(9)
	v_mov_b32_e32 v36, v46
	v_mov_b32_e32 v37, v47
	v_mov_b32_e32 v38, v48
	v_mov_b32_e32 v39, v49
	s_waitcnt vmcnt(8)
	v_mov_b32_e32 v46, v33
	v_mov_b32_e32 v42, v35
	s_andn2_b64 exec, exec, s[8:9]
	s_cbranch_execz .LBB0_503
	s_branch .LBB0_500
